# mseq chunk loop: relaxed vmcnt immediates (count the state stores), removed pre-reload vmcnt(6) so k/v prefetch stays 3 chunks deep instead of 2
# speedup vs baseline: 1.0009x; 1.0009x over previous
.LBB0_645:
	ds_read2_b32 v[98:99], v83 offset1:32
	s_waitcnt vmcnt(11)
	v_and_b32_e32 v131, 0xffff0000, v4
	v_lshlrev_b32_e32 v109, 16, v4
	v_lshlrev_b32_e32 v133, 16, v5
	s_waitcnt lgkmcnt(0)
	v_mul_f32_e32 v131, v98, v131
	v_mul_f32_e32 v109, v98, v109
	v_cvt_pk_bf16_f32 v132, v109, v131
	v_and_b32_e32 v131, 0xffff0000, v5
	v_mul_f32_e32 v109, v98, v133
	v_mul_f32_e32 v131, v98, v131
	v_cvt_pk_bf16_f32 v133, v109, v131
	v_lshlrev_b32_e32 v109, 16, v6
	v_and_b32_e32 v131, 0xffff0000, v6
	v_mul_f32_e32 v109, v98, v109
	v_mul_f32_e32 v131, v98, v131
	v_cvt_pk_bf16_f32 v134, v109, v131
	v_lshlrev_b32_e32 v109, 16, v7
	v_and_b32_e32 v131, 0xffff0000, v7
	v_mul_f32_e32 v109, v98, v109
	v_mul_f32_e32 v98, v98, v131
	v_cvt_pk_bf16_f32 v135, v109, v98
	s_waitcnt vmcnt(9)
	v_lshlrev_b32_e32 v98, 16, v8
	v_and_b32_e32 v109, 0xffff0000, v8
	v_mul_f32_e32 v98, v99, v98
	v_mul_f32_e32 v109, v99, v109
	v_cvt_pk_bf16_f32 v136, v98, v109
	v_lshlrev_b32_e32 v98, 16, v9
	v_and_b32_e32 v109, 0xffff0000, v9
	v_mul_f32_e32 v98, v99, v98
	v_mul_f32_e32 v109, v99, v109
	v_cvt_pk_bf16_f32 v137, v98, v109
	v_lshlrev_b32_e32 v98, 16, v10
	v_and_b32_e32 v109, 0xffff0000, v10
	v_mul_f32_e32 v98, v99, v98
	v_mul_f32_e32 v109, v99, v109
	v_cvt_pk_bf16_f32 v138, v98, v109
	v_lshlrev_b32_e32 v98, 16, v11
	v_and_b32_e32 v109, 0xffff0000, v11
	v_mul_f32_e32 v98, v99, v98
	v_mul_f32_e32 v99, v99, v109
	v_cvt_pk_bf16_f32 v139, v98, v99
	ds_write_b128 v118, v[132:135]
	ds_write_b128 v118, v[136:139] offset:8704
	s_and_saveexec_b64 s[16:17], s[70:71]
	s_cbranch_execz .LBB0_647
	s_waitcnt vmcnt(9)
	ds_write_b128 v119, v[16:19] offset:34816

.LBB0_651:
	s_cmp_gt_u32 s13, 27
	s_cselect_b64 s[16:17], -1, 0
	s_and_b64 vcc, exec, s[16:17]
	v_lshl_add_u64 v[104:105], s[82:83], 0, v[86:87]
	v_lshl_add_u64 v[96:97], s[82:83], 0, v[88:89]
	s_waitcnt lgkmcnt(0)
	s_barrier
	s_cbranch_vccnz .LBB0_653
	v_add_co_u32_e32 v4, vcc, 0xea40000, v104
	s_nop 1
	v_addc_co_u32_e32 v5, vcc, 0, v105, vcc
	v_add_co_u32_e32 v8, vcc, 0xea48000, v104
	s_nop 1
	v_addc_co_u32_e32 v9, vcc, 0, v105, vcc
	s_nop 0
	v_add_co_u32_e32 v16, vcc, 0xfb00000, v96
	global_load_dwordx4 v[4:7], v[4:5], off
	s_nop 0
	global_load_dwordx4 v[8:11], v[8:9], off
	v_addc_co_u32_e32 v17, vcc, 0, v97, vcc
	global_load_dwordx4 v[16:19], v[16:17], off
.LBB0_653:
	v_mov_b32_e32 v85, s8
	ds_read_b32 v106, v85
	v_add_u32_e32 v131, 0, v120
	v_add_u32_e32 v85, 0, v117
	s_mov_b32 s94, s92
	s_mov_b32 s95, s92
	s_waitcnt lgkmcnt(0)
	v_pk_mul_f32 v[58:59], v[58:59], v[106:107] op_sel_hi:[1,0]
	v_pk_mul_f32 v[56:57], v[56:57], v[106:107] op_sel_hi:[1,0]
	v_pk_mul_f32 v[62:63], v[62:63], v[106:107] op_sel_hi:[1,0]
	v_pk_mul_f32 v[60:61], v[60:61], v[106:107] op_sel_hi:[1,0]
	v_pk_mul_f32 v[54:55], v[54:55], v[106:107] op_sel_hi:[1,0]
	v_pk_mul_f32 v[52:53], v[52:53], v[106:107] op_sel_hi:[1,0]
	ds_read_b64_tr_b16 v[106:107], v131
	ds_read_b64_tr_b16 v[108:109], v125
	ds_read_b64_tr_b16 v[134:135], v126 offset:34816
	ds_read_b64_tr_b16 v[138:139], v126 offset:34848
	ds_read_b64_tr_b16 v[132:133], v85 offset:34816
	ds_read_b64_tr_b16 v[136:137], v85 offset:34848
	s_waitcnt lgkmcnt(1)
	v_mfma_f32_16x16x32_bf16 v[56:59], v[106:109], v[132:135], v[56:59]
	s_mov_b32 s93, s92
	v_mov_b64_e32 v[134:135], s[94:95]
	v_mov_b64_e32 v[132:133], s[92:93]
	s_waitcnt lgkmcnt(0)
	v_mfma_f32_16x16x32_bf16 v[60:63], v[106:109], v[136:139], v[60:63]
	v_mfma_f32_16x16x32_bf16 v[106:109], v[106:109], v[132:135], v[52:55]
	ds_read_b64_tr_b16 v[136:137], v127
	ds_read_b64_tr_b16 v[138:139], v128
	s_nop 0
	ds_read_b64_tr_b16 v[54:55], v130 offset:34816
	ds_read_b64_tr_b16 v[142:143], v130 offset:34848
	ds_read_b64_tr_b16 v[52:53], v129 offset:34816
	ds_read_b64_tr_b16 v[140:141], v129 offset:34848
	s_waitcnt lgkmcnt(1)
	v_mfma_f32_16x16x32_bf16 v[52:55], v[136:139], v[52:55], v[56:59]
	v_mfma_f32_16x16x32_bf16 v[56:59], v[136:139], v[132:135], v[106:109]
	ds_read2_b32 v[134:135], v83 offset0:64 offset1:96
	s_waitcnt vmcnt(11)
	v_and_b32_e32 v132, 0xffff0000, v15
	s_waitcnt vmcnt(9)
	v_and_b32_e32 v133, 0xffff0000, v20
	v_lshlrev_b32_e32 v106, 16, v12
	v_and_b32_e32 v107, 0xffff0000, v12
	s_waitcnt lgkmcnt(0)
	v_mul_f32_e32 v106, v134, v106
	v_mul_f32_e32 v107, v134, v107
	v_cvt_pk_bf16_f32 v106, v106, v107
	v_lshlrev_b32_e32 v107, 16, v13
	v_and_b32_e32 v108, 0xffff0000, v13
	v_mul_f32_e32 v107, v134, v107
	v_mul_f32_e32 v108, v134, v108
	v_cvt_pk_bf16_f32 v107, v107, v108
	v_lshlrev_b32_e32 v108, 16, v14
	v_and_b32_e32 v109, 0xffff0000, v14
	v_mul_f32_e32 v108, v134, v108
	v_mul_f32_e32 v109, v134, v109
	v_cvt_pk_bf16_f32 v108, v108, v109
	v_lshlrev_b32_e32 v109, 16, v15
	v_mul_f32_e32 v109, v134, v109
	v_mul_f32_e32 v132, v134, v132
	v_cvt_pk_bf16_f32 v109, v109, v132
	v_lshlrev_b32_e32 v132, 16, v20
	v_mul_f32_e32 v132, v135, v132
	v_mul_f32_e32 v133, v135, v133
	v_cvt_pk_bf16_f32 v132, v132, v133
	v_lshlrev_b32_e32 v133, 16, v21
	v_and_b32_e32 v134, 0xffff0000, v21
	v_mul_f32_e32 v133, v135, v133
	v_mul_f32_e32 v134, v135, v134
	v_mfma_f32_16x16x32_bf16 v[60:63], v[136:139], v[140:143], v[60:63]
	v_cvt_pk_bf16_f32 v133, v133, v134
	v_lshlrev_b32_e32 v134, 16, v22
	v_and_b32_e32 v136, 0xffff0000, v22
	v_mul_f32_e32 v134, v135, v134
	v_mul_f32_e32 v136, v135, v136
	v_cvt_pk_bf16_f32 v134, v134, v136
	v_lshlrev_b32_e32 v136, 16, v23
	v_and_b32_e32 v137, 0xffff0000, v23
	v_mul_f32_e32 v136, v135, v136
	v_mul_f32_e32 v135, v135, v137
	v_cvt_pk_bf16_f32 v135, v136, v135
	ds_write_b128 v118, v[106:109] offset:17408
	ds_write_b128 v118, v[132:135] offset:26112
	s_and_saveexec_b64 s[18:19], s[70:71]
	s_cbranch_execz .LBB0_655
	s_waitcnt vmcnt(9)
	ds_write_b128 v119, v[28:31] offset:39936

.LBB0_657:
	s_or_b64 exec, exec, s[18:19]
	s_cmp_gt_u32 s13, 26
	s_waitcnt lgkmcnt(0)
	s_barrier
	s_cbranch_scc1 .LBB0_659
	v_add_co_u32_e32 v12, vcc, 0xea50000, v104
	s_nop 1
	v_addc_co_u32_e32 v13, vcc, 0, v105, vcc
	v_add_co_u32_e32 v20, vcc, 0xea58000, v104
	s_nop 1
	v_addc_co_u32_e32 v21, vcc, 0, v105, vcc
	s_nop 0
	v_add_co_u32_e32 v28, vcc, 0xfb20000, v96
	global_load_dwordx4 v[12:15], v[12:13], off
	s_nop 0
	global_load_dwordx4 v[20:23], v[20:21], off
	v_addc_co_u32_e32 v29, vcc, 0, v97, vcc
	global_load_dwordx4 v[28:31], v[28:29], off
.LBB0_659:
	v_mov_b32_e32 v132, s8
	ds_read_b32 v132, v132 offset:4
	s_mov_b32 s94, s92
	s_mov_b32 s95, s92
	s_mov_b32 s93, s92
	s_waitcnt lgkmcnt(0)
	v_pk_mul_f32 v[54:55], v[54:55], v[132:133] op_sel_hi:[1,0]
	v_pk_mul_f32 v[52:53], v[52:53], v[132:133] op_sel_hi:[1,0]
	v_pk_mul_f32 v[62:63], v[62:63], v[132:133] op_sel_hi:[1,0]
	v_pk_mul_f32 v[60:61], v[60:61], v[132:133] op_sel_hi:[1,0]
	v_pk_mul_f32 v[58:59], v[58:59], v[132:133] op_sel_hi:[1,0]
	v_pk_mul_f32 v[56:57], v[56:57], v[132:133] op_sel_hi:[1,0]
	ds_read_b64_tr_b16 v[132:133], v131 offset:17408
	ds_read_b64_tr_b16 v[134:135], v125 offset:17408
	ds_read_b64_tr_b16 v[138:139], v126 offset:39936
	ds_read_b64_tr_b16 v[142:143], v126 offset:39968
	ds_read_b64_tr_b16 v[136:137], v85 offset:39936
	ds_read_b64_tr_b16 v[140:141], v85 offset:39968
	s_waitcnt lgkmcnt(1)
	v_mfma_f32_16x16x32_bf16 v[52:55], v[132:135], v[136:139], v[52:55]
	v_mov_b64_e32 v[138:139], s[94:95]
	v_mov_b64_e32 v[136:137], s[92:93]
	s_waitcnt lgkmcnt(0)
	v_mfma_f32_16x16x32_bf16 v[60:63], v[132:135], v[140:143], v[60:63]
	v_mfma_f32_16x16x32_bf16 v[56:59], v[132:135], v[136:139], v[56:59]
	ds_read_b64_tr_b16 v[132:133], v127 offset:17408
	ds_read_b64_tr_b16 v[134:135], v128 offset:17408
	ds_read_b64_tr_b16 v[142:143], v130 offset:39936
	ds_read_b64_tr_b16 v[146:147], v130 offset:39968
	ds_read_b64_tr_b16 v[140:141], v129 offset:39936
	ds_read_b64_tr_b16 v[144:145], v129 offset:39968
	s_waitcnt lgkmcnt(4)
	v_mfma_f32_16x16x32_bf16 v[56:59], v[132:135], v[136:139], v[56:59]
	ds_read2_b32 v[138:139], v83 offset0:128 offset1:160
	s_waitcnt vmcnt(11)
	v_and_b32_e32 v136, 0xffff0000, v27
	s_waitcnt vmcnt(9)
	v_and_b32_e32 v137, 0xffff0000, v32
	s_waitcnt lgkmcnt(2)
	v_mfma_f32_16x16x32_bf16 v[52:55], v[132:135], v[140:143], v[52:55]
	v_and_b32_e32 v140, 0xffff0000, v34
	s_waitcnt lgkmcnt(0)
	v_mul_f32_e32 v136, v138, v136
	v_mul_f32_e32 v137, v139, v137
	v_mfma_f32_16x16x32_bf16 v[60:63], v[132:135], v[144:147], v[60:63]
	v_lshlrev_b32_e32 v132, 16, v24
	v_and_b32_e32 v133, 0xffff0000, v24
	v_mul_f32_e32 v132, v138, v132
	v_mul_f32_e32 v133, v138, v133
	v_cvt_pk_bf16_f32 v132, v132, v133
	v_lshlrev_b32_e32 v133, 16, v25
	v_and_b32_e32 v134, 0xffff0000, v25
	v_mul_f32_e32 v133, v138, v133
	v_mul_f32_e32 v134, v138, v134
	v_cvt_pk_bf16_f32 v133, v133, v134
	v_lshlrev_b32_e32 v134, 16, v26
	v_and_b32_e32 v135, 0xffff0000, v26
	v_mul_f32_e32 v134, v138, v134
	v_mul_f32_e32 v135, v138, v135
	v_cvt_pk_bf16_f32 v134, v134, v135
	v_lshlrev_b32_e32 v135, 16, v27
	v_mul_f32_e32 v135, v138, v135
	v_cvt_pk_bf16_f32 v135, v135, v136
	v_lshlrev_b32_e32 v136, 16, v32
	v_mul_f32_e32 v136, v139, v136
	v_cvt_pk_bf16_f32 v136, v136, v137
	v_lshlrev_b32_e32 v137, 16, v33
	v_and_b32_e32 v138, 0xffff0000, v33
	v_mul_f32_e32 v137, v139, v137
	v_mul_f32_e32 v138, v139, v138
	v_cvt_pk_bf16_f32 v137, v137, v138
	v_lshlrev_b32_e32 v138, 16, v34
	v_mul_f32_e32 v138, v139, v138
	v_mul_f32_e32 v140, v139, v140
	v_cvt_pk_bf16_f32 v138, v138, v140
	v_lshlrev_b32_e32 v140, 16, v35
	v_and_b32_e32 v141, 0xffff0000, v35
	v_mul_f32_e32 v140, v139, v140
	v_mul_f32_e32 v139, v139, v141
	v_cvt_pk_bf16_f32 v139, v140, v139
	ds_write_b128 v118, v[132:135]
	ds_write_b128 v118, v[136:139] offset:8704
	s_and_saveexec_b64 s[18:19], s[70:71]
	s_cbranch_execz .LBB0_661
	s_waitcnt vmcnt(9)
	ds_write_b128 v119, v[40:43] offset:34816

.LBB0_663:
	s_or_b64 exec, exec, s[18:19]
	s_cmp_gt_u32 s13, 25
	s_waitcnt lgkmcnt(0)
	s_barrier
	s_cbranch_scc1 .LBB0_665
	v_add_co_u32_e32 v24, vcc, 0xea60000, v104
	s_nop 1
	v_addc_co_u32_e32 v25, vcc, 0, v105, vcc
	v_add_co_u32_e32 v32, vcc, 0xea68000, v104
	s_nop 1
	v_addc_co_u32_e32 v33, vcc, 0, v105, vcc
	s_nop 0
	v_add_co_u32_e32 v40, vcc, 0xfb40000, v96
	global_load_dwordx4 v[24:27], v[24:25], off
	s_nop 0
	global_load_dwordx4 v[32:35], v[32:33], off
	v_addc_co_u32_e32 v41, vcc, 0, v97, vcc
	global_load_dwordx4 v[40:43], v[40:41], off
.LBB0_665:
	v_mov_b32_e32 v132, s8
	ds_read_b32 v132, v132 offset:8
	s_mov_b32 s94, s92
	s_mov_b32 s95, s92
	s_mov_b32 s93, s92
	s_waitcnt lgkmcnt(0)
	v_pk_mul_f32 v[54:55], v[54:55], v[132:133] op_sel_hi:[1,0]
	v_pk_mul_f32 v[52:53], v[52:53], v[132:133] op_sel_hi:[1,0]
	v_pk_mul_f32 v[62:63], v[62:63], v[132:133] op_sel_hi:[1,0]
	v_pk_mul_f32 v[60:61], v[60:61], v[132:133] op_sel_hi:[1,0]
	v_pk_mul_f32 v[58:59], v[58:59], v[132:133] op_sel_hi:[1,0]
	v_pk_mul_f32 v[56:57], v[56:57], v[132:133] op_sel_hi:[1,0]
	ds_read_b64_tr_b16 v[132:133], v131
	ds_read_b64_tr_b16 v[134:135], v125
	ds_read_b64_tr_b16 v[138:139], v126 offset:34816
	ds_read_b64_tr_b16 v[142:143], v126 offset:34848
	ds_read_b64_tr_b16 v[136:137], v85 offset:34816
	ds_read_b64_tr_b16 v[140:141], v85 offset:34848
	s_waitcnt lgkmcnt(1)
	v_mfma_f32_16x16x32_bf16 v[52:55], v[132:135], v[136:139], v[52:55]
	v_mov_b64_e32 v[138:139], s[94:95]
	v_mov_b64_e32 v[136:137], s[92:93]
	s_waitcnt lgkmcnt(0)
	v_mfma_f32_16x16x32_bf16 v[60:63], v[132:135], v[140:143], v[60:63]
	v_mfma_f32_16x16x32_bf16 v[56:59], v[132:135], v[136:139], v[56:59]
	ds_read_b64_tr_b16 v[132:133], v127
	ds_read_b64_tr_b16 v[134:135], v128
	ds_read_b64_tr_b16 v[142:143], v130 offset:34816
	ds_read_b64_tr_b16 v[146:147], v130 offset:34848
	ds_read_b64_tr_b16 v[140:141], v129 offset:34816
	ds_read_b64_tr_b16 v[144:145], v129 offset:34848
	s_waitcnt lgkmcnt(4)
	v_mfma_f32_16x16x32_bf16 v[56:59], v[132:135], v[136:139], v[56:59]
	ds_read2_b32 v[138:139], v83 offset0:192 offset1:224
	s_waitcnt vmcnt(8)
	v_and_b32_e32 v136, 0xffff0000, v39
	s_waitcnt vmcnt(6)
	v_and_b32_e32 v137, 0xffff0000, v44
	s_waitcnt lgkmcnt(2)
	v_mfma_f32_16x16x32_bf16 v[52:55], v[132:135], v[140:143], v[52:55]
	v_and_b32_e32 v140, 0xffff0000, v46
	s_waitcnt lgkmcnt(0)
	v_mul_f32_e32 v136, v138, v136
	v_mul_f32_e32 v137, v139, v137
	v_mfma_f32_16x16x32_bf16 v[60:63], v[132:135], v[144:147], v[60:63]
	v_lshlrev_b32_e32 v132, 16, v36
	v_and_b32_e32 v133, 0xffff0000, v36
	v_mul_f32_e32 v132, v138, v132
	v_mul_f32_e32 v133, v138, v133
	v_cvt_pk_bf16_f32 v132, v132, v133
	v_lshlrev_b32_e32 v133, 16, v37
	v_and_b32_e32 v134, 0xffff0000, v37
	v_mul_f32_e32 v133, v138, v133
	v_mul_f32_e32 v134, v138, v134
	v_cvt_pk_bf16_f32 v133, v133, v134
	v_lshlrev_b32_e32 v134, 16, v38
	v_and_b32_e32 v135, 0xffff0000, v38
	v_mul_f32_e32 v134, v138, v134
	v_mul_f32_e32 v135, v138, v135
	v_cvt_pk_bf16_f32 v134, v134, v135
	v_lshlrev_b32_e32 v135, 16, v39
	v_mul_f32_e32 v135, v138, v135
	v_cvt_pk_bf16_f32 v135, v135, v136
	v_lshlrev_b32_e32 v136, 16, v44
	v_mul_f32_e32 v136, v139, v136
	v_cvt_pk_bf16_f32 v136, v136, v137
	v_lshlrev_b32_e32 v137, 16, v45
	v_and_b32_e32 v138, 0xffff0000, v45
	v_mul_f32_e32 v137, v139, v137
	v_mul_f32_e32 v138, v139, v138
	v_cvt_pk_bf16_f32 v137, v137, v138
	v_lshlrev_b32_e32 v138, 16, v46
	v_mul_f32_e32 v138, v139, v138
	v_mul_f32_e32 v140, v139, v140
	v_cvt_pk_bf16_f32 v138, v138, v140
	v_lshlrev_b32_e32 v140, 16, v47
	v_and_b32_e32 v141, 0xffff0000, v47
	v_mul_f32_e32 v140, v139, v140
	v_mul_f32_e32 v139, v139, v141
	v_cvt_pk_bf16_f32 v139, v140, v139
	ds_write_b128 v118, v[132:135] offset:17408
	ds_write_b128 v118, v[136:139] offset:26112
	s_and_saveexec_b64 s[18:19], s[70:71]
	s_cbranch_execz .LBB0_667
	s_waitcnt vmcnt(6)
	ds_write_b128 v119, v[48:51] offset:39936
